# gemm_up conv-gate epilogue: 15-way register select chains replaced by per-half moves; per-store 64-bit VALU address math replaced by scalar row bases + one lane offset
# speedup vs baseline: 1.0199x; 1.0075x over previous
.LBB0_2182:
	s_or_b64 exec, exec, s[0:1]
	v_add_u32_e32 v139, v168, v183
	s_mov_b64 s[0:1], 0xb2d4000
	ds_write_b32 v139, v186
	v_lshl_add_u32 v139, v254, 2, v167
	v_lshl_add_u64 v[128:129], v[232:233], 0, s[0:1]
	s_waitcnt lgkmcnt(0)
	s_barrier
	v_cmp_eq_u32_e64 s[0:1], 1, v166
	ds_read2st64_b32 v[166:167], v139 offset0:4 offset1:5
	s_cmp_lt_i32 s8, 16
	ds_read2_b32 v[186:187], v139 offset0:32 offset1:96
	s_movk_i32 s4, 0x80
	s_cselect_b64 s[2:3], -1, 0
	v_cmp_gt_u32_e64 s[4:5], s4, v252
	s_and_b64 s[4:5], s[2:3], s[4:5]
	s_and_b64 s[0:1], s[2:3], s[0:1]
	s_waitcnt lgkmcnt(1)
	v_cndmask_b32_e64 v139, 0, v167, s[4:5]
	v_and_b32_e32 v167, 64, v244
	v_xor_b32_e32 v147, 32, v244
	v_add_u32_e32 v167, 64, v167
	s_waitcnt lgkmcnt(0)
	v_cndmask_b32_e64 v217, 0, v186, s[0:1]
	v_cndmask_b32_e64 v218, 0, v187, s[0:1]
	v_cmp_lt_i32_e64 s[0:1], v147, v167
	s_waitcnt vmcnt(3)
	v_fma_f32 v223, v114, v153, v148
	v_fmac_f32_e32 v223, v115, v154
	v_cndmask_b32_e64 v147, v244, v147, s[0:1]
	v_lshlrev_b32_e32 v147, 2, v147
	ds_bpermute_b32 v219, v147, v80
	v_fma_f32 v224, v117, v153, v148
	v_fmac_f32_e32 v224, v118, v154
	v_fmac_f32_e32 v224, v119, v155
	ds_bpermute_b32 v220, v147, v64
	ds_bpermute_b32 v207, v147, v127
	v_and_b32_e32 v221, 0xffffff80, v252
	v_lshl_or_b32 v221, v253, 2, v221
	v_cndmask_b32_e64 v166, 0, v166, s[4:5]
	ds_bpermute_b32 v188, v147, v95
	ds_bpermute_b32 v168, v147, v63
	ds_bpermute_b32 v208, v147, v48
	ds_bpermute_b32 v187, v147, v16
	ds_bpermute_b32 v205, v147, v111
	ds_bpermute_b32 v186, v147, v79
	ds_bpermute_b32 v167, v147, v47
	ds_bpermute_b32 v206, v147, v32
	ds_bpermute_b32 v183, v147, v0
	s_nop 0
	s_nop 1
	s_nop 1
	s_nop 1
	s_nop 1
	s_nop 1
	ds_bpermute_b32 v146, v147, v146
	s_waitcnt lgkmcnt(0)
	v_cndmask_b32_e32 v146, v146, v217, vcc
	v_fma_f32 v146, v153, v146, v148
	v_fmac_f32_e32 v146, v154, v112
	v_fma_f32 v217, v153, v112, v148
	v_fmac_f32_e32 v146, v113, v155
	v_fmac_f32_e32 v217, v113, v154
	v_fmac_f32_e32 v217, v114, v155
	s_nop 1
	s_nop 1
	s_nop 1
	s_nop 1
	s_nop 1
	s_nop 1
	s_nop 1
	s_nop 1
	s_nop 1
	s_nop 1
	s_nop 1
	ds_bpermute_b32 v144, v147, v144
	s_waitcnt lgkmcnt(0)
	v_fmac_f32_e32 v223, v155, v144
	v_fma_f32 v144, v116, v153, v148
	v_fmac_f32_e32 v144, v117, v154
	v_fmac_f32_e32 v144, v118, v155
	s_nop 0
	s_nop 1
	s_nop 1
	s_nop 1
	s_nop 1
	s_nop 1
	s_nop 1
	s_nop 1
	s_nop 1
	s_nop 1
	s_nop 1
	s_nop 1
	s_nop 1
	ds_bpermute_b32 v142, v147, v142
	s_waitcnt lgkmcnt(0)
	v_fma_f32 v142, v153, v142, v148
	v_fmac_f32_e32 v142, v116, v154
	v_fmac_f32_e32 v142, v117, v155
	s_nop 1
	s_nop 1
	s_nop 1
	s_nop 1
	s_nop 1
	s_nop 1
	s_nop 1
	s_nop 1
	s_nop 1
	s_nop 1
	s_nop 1
	s_nop 1
	s_nop 1
	ds_bpermute_b32 v140, v147, v140
	s_nop 0
	s_nop 1
	s_nop 1
	s_nop 1
	s_nop 1
	s_nop 1
	s_nop 1
	s_nop 1
	s_nop 1
	s_nop 1
	s_nop 1
	s_nop 1
	s_nop 1
	s_nop 1
	s_nop 1
	ds_bpermute_b32 v136, v147, v136
	s_nop 0
	s_nop 1
	s_nop 1
	s_nop 1
	s_nop 1
	s_nop 1
	s_nop 1
	s_nop 1
	s_nop 1
	s_nop 1
	s_nop 1
	s_nop 1
	s_nop 1
	s_nop 1
	s_nop 1
	ds_bpermute_b32 v134, v147, v134
	s_nop 0
	s_nop 1
	s_nop 1
	s_nop 1
	s_nop 1
	s_nop 1
	s_nop 1
	s_nop 1
	s_nop 1
	s_nop 1
	s_nop 1
	s_nop 1
	s_nop 1
	s_nop 1
	s_nop 1
	ds_bpermute_b32 v138, v147, v138
	s_nop 0
	v_fma_f32 v112, v126, v153, v148
	v_fmac_f32_e32 v112, v127, v154
	s_nop 1
	s_nop 1
	v_fma_f32 v116, v122, v153, v148
	v_fmac_f32_e32 v116, v123, v154
	v_fma_f32 v117, v121, v153, v148
	s_waitcnt lgkmcnt(1)
	v_fmac_f32_e32 v116, v155, v134
	v_fma_f32 v118, v118, v153, v148
	v_fmac_f32_e32 v118, v119, v154
	v_fma_f32 v119, v153, v136, v148
	v_fmac_f32_e32 v119, v120, v154
	v_fma_f32 v120, v120, v153, v148
	v_fmac_f32_e32 v119, v121, v155
	v_fmac_f32_e32 v120, v121, v154
	s_waitcnt vmcnt(0)
	v_fma_f32 v134, v96, v150, v149
	v_fmac_f32_e32 v117, v122, v154
	v_fmac_f32_e32 v120, v122, v155
	v_fmac_f32_e32 v117, v123, v155
	ds_bpermute_b32 v122, v147, v215
	ds_bpermute_b32 v123, v147, v214
	v_fma_f32 v136, v97, v150, v149
	v_fmac_f32_e32 v136, v98, v151
	v_fmac_f32_e32 v136, v99, v152
	v_fmac_f32_e32 v134, v97, v151
	v_fmac_f32_e32 v118, v155, v140
	ds_bpermute_b32 v132, v147, v132
	v_fma_f32 v222, v113, v153, v148
	v_fmac_f32_e32 v222, v114, v154
	v_fmac_f32_e32 v222, v115, v155
	s_waitcnt lgkmcnt(3)
	v_fma_f32 v115, v153, v138, v148
	s_waitcnt lgkmcnt(0)
	v_cndmask_b32_e32 v121, v219, v132, vcc
	v_fmac_f32_e32 v112, v155, v121
	ds_bpermute_b32 v121, v147, v216
	v_fmac_f32_e32 v115, v124, v154
	v_fma_f32 v114, v124, v153, v148
	v_fmac_f32_e32 v115, v125, v155
	v_fmac_f32_e32 v114, v125, v154
	s_waitcnt lgkmcnt(0)
	v_cndmask_b32_e32 v121, v121, v218, vcc
	v_fma_f32 v121, v150, v121, v149
	v_fmac_f32_e32 v121, v96, v151
	v_mul_f32_e32 v96, 0x3d372713, v146
	v_mul_f32_e32 v96, v146, v96
	v_fma_f32 v96, v146, v96, v146
	v_mul_f32_e32 v96, 0xbfcc422a, v96
	v_mul_f32_e32 v96, 0x3fb8aa3b, v96
	v_exp_f32_e32 v96, v96
	v_fma_f32 v113, v125, v153, v148
	ds_bpermute_b32 v124, v147, v213
	ds_bpermute_b32 v125, v147, v212
	v_add_f32_e32 v96, 1.0, v96
	v_fmac_f32_e32 v113, v126, v154
	ds_bpermute_b32 v132, v147, v209
	v_fma_f32 v209, v102, v150, v149
	v_rcp_f32_e32 v96, v96
	v_fmac_f32_e32 v113, v127, v155
	ds_bpermute_b32 v127, v147, v210
	v_fmac_f32_e32 v209, v103, v151
	s_waitcnt lgkmcnt(3)
	v_fmac_f32_e32 v209, v152, v124
	s_waitcnt lgkmcnt(2)
	v_fma_f32 v124, v150, v125, v149
	v_fma_f32 v138, v98, v150, v149
	v_fmac_f32_e32 v124, v104, v151
	v_fma_f32 v104, v104, v150, v149
	v_fmac_f32_e32 v121, v97, v152
	v_fmac_f32_e32 v138, v99, v151
	v_fmac_f32_e32 v124, v105, v152
	v_fmac_f32_e32 v104, v105, v151
	v_fma_f32 v105, v105, v150, v149
	v_fma_f32 v99, v110, v150, v149
	v_mul_f32_e32 v96, v146, v96
	v_fmac_f32_e32 v138, v152, v122
	v_fma_f32 v122, v150, v123, v149
	v_fmac_f32_e32 v104, v106, v152
	v_fmac_f32_e32 v105, v106, v151
	v_fma_f32 v106, v106, v150, v149
	s_waitcnt lgkmcnt(1)
	v_cndmask_b32_e32 v97, v220, v132, vcc
	v_fmac_f32_e32 v99, v111, v151
	v_mul_f32_e32 v96, v121, v96
	v_fmac_f32_e32 v122, v100, v151
	v_fma_f32 v123, v100, v150, v149
	v_fmac_f32_e32 v105, v107, v152
	v_fmac_f32_e32 v106, v107, v151
	s_waitcnt lgkmcnt(0)
	v_fma_f32 v107, v150, v127, v149
	v_fmac_f32_e32 v99, v152, v97
	v_bfe_u32 v97, v96, 16, 1
	v_fmac_f32_e32 v122, v101, v152
	v_fmac_f32_e32 v123, v101, v151
	v_fma_f32 v140, v101, v150, v149
	v_fmac_f32_e32 v107, v108, v151
	v_fma_f32 v101, v108, v150, v149
	v_add3_u32 v108, v96, v97, s89
	v_mul_f32_e32 v96, 0x3d372713, v217
	v_mul_f32_e32 v96, v217, v96
	v_fma_f32 v96, v217, v96, v217
	v_mul_f32_e32 v96, 0xbfcc422a, v96
	v_mul_f32_e32 v96, 0x3fb8aa3b, v96
	v_fmac_f32_e32 v107, v109, v152
	v_fmac_f32_e32 v101, v109, v151
	v_fma_f32 v100, v109, v150, v149
	v_exp_f32_e32 v109, v96
	v_fmac_f32_e32 v134, v98, v152
	v_fmac_f32_e32 v140, v102, v151
	v_mul_u32_u24_e32 v98, 0x1600, v221
	v_lshl_add_u32 v98, v130, 1, v98
	v_readfirstlane_b32 s18, v128
	v_readfirstlane_b32 s19, v129
	s_lshl_b32 s20, s8, 8
	s_mul_i32 s20, s20, 0x1600
	s_add_u32 s18, s18, s20
	s_addc_u32 s19, s19, 0
	v_add_f32_e32 v109, 1.0, v109
	v_rcp_f32_e32 v109, v109
	v_fmac_f32_e32 v123, v102, v152
	v_fmac_f32_e32 v140, v103, v152
	s_add_u32 s20, s18, 0x0
	s_addc_u32 s21, s19, 0
	global_store_short_d16_hi v98, v108, s[20:21]
	v_mul_f32_e32 v103, v217, v109
	v_mul_f32_e32 v109, 0x3d372713, v222
	v_mul_f32_e32 v109, v222, v109
	v_fma_f32 v109, v222, v109, v222
	v_mul_f32_e32 v109, 0xbfcc422a, v109
	v_mul_f32_e32 v109, 0x3fb8aa3b, v109
	v_exp_f32_e32 v109, v109
	v_mul_f32_e32 v103, v134, v103
	v_bfe_u32 v108, v103, 16, 1
	v_add_f32_e32 v109, 1.0, v109
	v_rcp_f32_e32 v109, v109
	v_add3_u32 v108, v103, v108, s89
	s_add_u32 s20, s18, 0x1600
	s_addc_u32 s21, s19, 0
	global_store_short_d16_hi v98, v108, s[20:21]
	v_mul_f32_e32 v103, v222, v109
	v_mul_f32_e32 v109, 0x3d372713, v223
	v_mul_f32_e32 v109, v223, v109
	v_fma_f32 v109, v223, v109, v223
	v_mul_f32_e32 v109, 0xbfcc422a, v109
	v_mul_f32_e32 v109, 0x3fb8aa3b, v109
	v_exp_f32_e32 v109, v109
	v_mul_f32_e32 v103, v136, v103
	v_bfe_u32 v108, v103, 16, 1
	v_add_f32_e32 v109, 1.0, v109
	v_rcp_f32_e32 v109, v109
	v_add3_u32 v108, v103, v108, s89
	v_fmac_f32_e32 v114, v126, v155
	ds_bpermute_b32 v126, v147, v211
	s_add_u32 s20, s18, 0x2c00
	s_addc_u32 s21, s19, 0
	global_store_short_d16_hi v98, v108, s[20:21]
	v_mul_f32_e32 v103, v223, v109
	v_mul_f32_e32 v103, v138, v103
	v_bfe_u32 v108, v103, 16, 1
	v_add3_u32 v108, v103, v108, s89
	v_fmac_f32_e32 v100, v110, v151
	s_waitcnt lgkmcnt(0)
	v_fmac_f32_e32 v106, v152, v126
	v_fmac_f32_e32 v101, v110, v152
	v_fmac_f32_e32 v100, v111, v152
	s_add_u32 s20, s18, 0x4200
	s_addc_u32 s21, s19, 0
	global_store_short_d16_hi v98, v108, s[20:21]
	v_mul_f32_e32 v103, 0x3d372713, v142
	v_mul_f32_e32 v103, v142, v103
	v_fma_f32 v103, v142, v103, v142
	v_mul_f32_e32 v103, 0xbfcc422a, v103
	v_mul_f32_e32 v103, 0x3fb8aa3b, v103
	v_exp_f32_e32 v103, v103
	s_nop 0
	v_add_f32_e32 v103, 1.0, v103
	v_rcp_f32_e32 v103, v103
	s_nop 0
	v_mul_f32_e32 v103, v142, v103
	v_mul_f32_e32 v103, v122, v103
	v_bfe_u32 v108, v103, 16, 1
	v_add3_u32 v108, v103, v108, s89
	s_add_u32 s20, s18, 0xb000
	s_addc_u32 s21, s19, 0
	global_store_short_d16_hi v98, v108, s[20:21]
	v_mul_f32_e32 v103, 0x3d372713, v144
	v_mul_f32_e32 v103, v144, v103
	v_fma_f32 v103, v144, v103, v144
	v_mul_f32_e32 v103, 0xbfcc422a, v103
	v_mul_f32_e32 v103, 0x3fb8aa3b, v103
	v_exp_f32_e32 v103, v103
	s_nop 0
	v_add_f32_e32 v103, 1.0, v103
	v_rcp_f32_e32 v103, v103
	s_nop 0
	v_mul_f32_e32 v103, v144, v103
	v_mul_f32_e32 v103, v123, v103
	v_bfe_u32 v108, v103, 16, 1
	v_add3_u32 v108, v103, v108, s89
	s_add_u32 s20, s18, 0xc600
	s_addc_u32 s21, s19, 0
	global_store_short_d16_hi v98, v108, s[20:21]
	v_mul_f32_e32 v103, 0x3d372713, v224
	v_mul_f32_e32 v103, v224, v103
	v_fma_f32 v103, v224, v103, v224
	v_mul_f32_e32 v103, 0xbfcc422a, v103
	v_mul_f32_e32 v103, 0x3fb8aa3b, v103
	v_exp_f32_e32 v103, v103
	s_nop 0
	v_add_f32_e32 v103, 1.0, v103
	v_rcp_f32_e32 v103, v103
	s_nop 0
	v_mul_f32_e32 v103, v224, v103
	v_mul_f32_e32 v103, v140, v103
	v_bfe_u32 v108, v103, 16, 1
	v_add3_u32 v108, v103, v108, s89
	s_add_u32 s20, s18, 0xdc00
	s_addc_u32 s21, s19, 0
	global_store_short_d16_hi v98, v108, s[20:21]
	v_mul_f32_e32 v103, 0x3d372713, v118
	v_mul_f32_e32 v103, v118, v103
	v_fma_f32 v103, v118, v103, v118
	v_mul_f32_e32 v103, 0xbfcc422a, v103
	v_mul_f32_e32 v103, 0x3fb8aa3b, v103
	v_exp_f32_e32 v103, v103
	s_nop 0
	v_add_f32_e32 v103, 1.0, v103
	v_rcp_f32_e32 v103, v103
	s_nop 0
	v_mul_f32_e32 v103, v118, v103
	v_mul_f32_e32 v103, v209, v103
	v_bfe_u32 v108, v103, 16, 1
	v_add3_u32 v108, v103, v108, s89
	s_add_u32 s20, s18, 0xf200
	s_addc_u32 s21, s19, 0
	global_store_short_d16_hi v98, v108, s[20:21]
	v_mul_f32_e32 v103, 0x3d372713, v119
	v_mul_f32_e32 v103, v119, v103
	v_fma_f32 v103, v119, v103, v119
	v_mul_f32_e32 v103, 0xbfcc422a, v103
	v_mul_f32_e32 v103, 0x3fb8aa3b, v103
	v_exp_f32_e32 v103, v103
	s_nop 0
	v_add_f32_e32 v103, 1.0, v103
	v_rcp_f32_e32 v103, v103
	s_nop 0
	v_mul_f32_e32 v103, v119, v103
	v_mul_f32_e32 v103, v124, v103
	v_bfe_u32 v108, v103, 16, 1
	v_add3_u32 v108, v103, v108, s89
	s_add_u32 s20, s18, 0x16000
	s_addc_u32 s21, s19, 0
	global_store_short_d16_hi v98, v108, s[20:21]
	v_mul_f32_e32 v103, 0x3d372713, v120
	v_mul_f32_e32 v103, v120, v103
	v_fma_f32 v103, v120, v103, v120
	v_mul_f32_e32 v103, 0xbfcc422a, v103
	v_mul_f32_e32 v103, 0x3fb8aa3b, v103
	v_exp_f32_e32 v103, v103
	s_nop 0
	v_add_f32_e32 v103, 1.0, v103
	v_rcp_f32_e32 v103, v103
	s_nop 0
	v_mul_f32_e32 v103, v120, v103
	v_mul_f32_e32 v103, v104, v103
	v_bfe_u32 v104, v103, 16, 1
	v_add3_u32 v104, v103, v104, s89
	s_add_u32 s20, s18, 0x17600
	s_addc_u32 s21, s19, 0
	global_store_short_d16_hi v98, v104, s[20:21]
	v_mul_f32_e32 v103, 0x3d372713, v117
	v_mul_f32_e32 v103, v117, v103
	v_fma_f32 v103, v117, v103, v117
	v_mul_f32_e32 v103, 0xbfcc422a, v103
	v_mul_f32_e32 v103, 0x3fb8aa3b, v103
	v_exp_f32_e32 v103, v103
	s_nop 0
	v_add_f32_e32 v103, 1.0, v103
	v_rcp_f32_e32 v103, v103
	s_nop 0
	v_mul_f32_e32 v103, v117, v103
	v_mul_f32_e32 v103, v105, v103
	v_bfe_u32 v104, v103, 16, 1
	v_add3_u32 v104, v103, v104, s89
	s_add_u32 s20, s18, 0x18c00
	s_addc_u32 s21, s19, 0
	global_store_short_d16_hi v98, v104, s[20:21]
	v_mul_f32_e32 v103, 0x3d372713, v116
	v_mul_f32_e32 v103, v116, v103
	v_fma_f32 v103, v116, v103, v116
	v_mul_f32_e32 v103, 0xbfcc422a, v103
	v_mul_f32_e32 v103, 0x3fb8aa3b, v103
	v_exp_f32_e32 v103, v103
	s_nop 0
	v_add_f32_e32 v103, 1.0, v103
	v_rcp_f32_e32 v103, v103
	s_nop 0
	v_mul_f32_e32 v103, v116, v103
	v_mul_f32_e32 v103, v106, v103
	v_bfe_u32 v104, v103, 16, 1
	v_add3_u32 v104, v103, v104, s89
	s_add_u32 s20, s18, 0x1a200
	s_addc_u32 s21, s19, 0
	global_store_short_d16_hi v98, v104, s[20:21]
	v_mul_f32_e32 v103, 0x3d372713, v115
	v_mul_f32_e32 v103, v115, v103
	v_fma_f32 v103, v115, v103, v115
	v_mul_f32_e32 v103, 0xbfcc422a, v103
	v_mul_f32_e32 v103, 0x3fb8aa3b, v103
	v_exp_f32_e32 v103, v103
	s_nop 0
	v_add_f32_e32 v103, 1.0, v103
	v_rcp_f32_e32 v103, v103
	s_nop 0
	v_mul_f32_e32 v103, v115, v103
	v_mul_f32_e32 v103, v107, v103
	v_bfe_u32 v104, v103, 16, 1
	v_add3_u32 v104, v103, v104, s89
	s_add_u32 s20, s18, 0x21000
	s_addc_u32 s21, s19, 0
	global_store_short_d16_hi v98, v104, s[20:21]
	v_mul_f32_e32 v103, 0x3d372713, v114
	v_mul_f32_e32 v103, v114, v103
	v_fma_f32 v103, v114, v103, v114
	v_mul_f32_e32 v103, 0xbfcc422a, v103
	v_mul_f32_e32 v103, 0x3fb8aa3b, v103
	v_exp_f32_e32 v103, v103
	s_nop 0
	v_add_f32_e32 v103, 1.0, v103
	v_rcp_f32_e32 v103, v103
	s_nop 0
	v_mul_f32_e32 v103, v114, v103
	v_mul_f32_e32 v101, v101, v103
	v_bfe_u32 v103, v101, 16, 1
	v_add3_u32 v101, v101, v103, s89
	s_add_u32 s20, s18, 0x22600
	s_addc_u32 s21, s19, 0
	global_store_short_d16_hi v98, v101, s[20:21]
	v_mul_f32_e32 v102, 0x3d372713, v113
	v_mul_f32_e32 v102, v113, v102
	v_fma_f32 v102, v113, v102, v113
	v_mul_f32_e32 v102, 0xbfcc422a, v102
	v_mul_f32_e32 v102, 0x3fb8aa3b, v102
	v_exp_f32_e32 v102, v102
	s_nop 0
	v_add_f32_e32 v102, 1.0, v102
	v_rcp_f32_e32 v102, v102
	s_nop 0
	v_mul_f32_e32 v102, v113, v102
	v_mul_f32_e32 v100, v100, v102
	v_bfe_u32 v102, v100, 16, 1
	v_add3_u32 v102, v100, v102, s89
	s_add_u32 s20, s18, 0x23c00
	s_addc_u32 s21, s19, 0
	global_store_short_d16_hi v98, v102, s[20:21]
	v_mul_f32_e32 v101, 0x3d372713, v112
	v_mul_f32_e32 v101, v112, v101
	v_fma_f32 v101, v112, v101, v112
	v_mul_f32_e32 v101, 0xbfcc422a, v101
	v_mul_f32_e32 v101, 0x3fb8aa3b, v101
	v_exp_f32_e32 v101, v101
	s_nop 0
	v_add_f32_e32 v101, 1.0, v101
	v_rcp_f32_e32 v101, v101
	s_nop 0
	v_mul_f32_e32 v101, v112, v101
	v_mul_f32_e32 v99, v99, v101
	v_bfe_u32 v101, v99, 16, 1
	v_add3_u32 v99, v99, v101, s89
	s_add_u32 s20, s18, 0x25200
	s_addc_u32 s21, s19, 0
	global_store_short_d16_hi v98, v99, s[20:21]
	ds_bpermute_b32 v101, v147, v203
	ds_bpermute_b32 v102, v147, v202
	ds_bpermute_b32 v100, v147, v204
	ds_bpermute_b32 v104, v147, v200
	v_fma_f32 v110, v82, v153, v148
	ds_bpermute_b32 v106, v147, v198
	v_fmac_f32_e32 v110, v83, v154
	s_waitcnt lgkmcnt(4)
	v_fmac_f32_e32 v110, v155, v101
	s_waitcnt lgkmcnt(3)
	v_fma_f32 v101, v153, v102, v148
	v_fma_f32 v102, v84, v153, v148
	v_fmac_f32_e32 v101, v84, v154
	v_fmac_f32_e32 v102, v85, v154
	v_fma_f32 v111, v85, v153, v148
	v_fma_f32 v109, v81, v153, v148
	v_fmac_f32_e32 v101, v85, v155
	v_fmac_f32_e32 v102, v86, v155
	v_fmac_f32_e32 v111, v86, v154
	v_fma_f32 v86, v86, v153, v148
	v_fma_f32 v85, v89, v153, v148
	ds_bpermute_b32 v105, v147, v199
	s_waitcnt lgkmcnt(3)
	v_cndmask_b32_e32 v100, v100, v207, vcc
	v_fma_f32 v108, v80, v153, v148
	v_fmac_f32_e32 v109, v82, v154
	v_fmac_f32_e32 v111, v87, v155
	v_fmac_f32_e32 v86, v87, v154
	s_waitcnt lgkmcnt(2)
	v_fma_f32 v87, v153, v104, v148
	v_fmac_f32_e32 v85, v90, v154
	v_fma_f32 v84, v90, v153, v148
	v_fma_f32 v100, v153, v100, v148
	v_fmac_f32_e32 v108, v81, v154
	v_fmac_f32_e32 v109, v83, v155
	v_fmac_f32_e32 v87, v88, v154
	v_fma_f32 v88, v88, v153, v148
	v_fmac_f32_e32 v85, v91, v155
	v_fmac_f32_e32 v84, v91, v154
	s_waitcnt lgkmcnt(1)
	v_fma_f32 v83, v153, v106, v148
	ds_bpermute_b32 v91, v147, v195
	v_fmac_f32_e32 v100, v80, v154
	v_fmac_f32_e32 v108, v82, v155
	v_fmac_f32_e32 v88, v89, v154
	v_fmac_f32_e32 v83, v92, v154
	v_fma_f32 v82, v92, v153, v148
	ds_bpermute_b32 v92, v147, v194
	ds_bpermute_b32 v107, v147, v197
	v_fmac_f32_e32 v100, v81, v155
	v_fmac_f32_e32 v88, v90, v155
	v_fmac_f32_e32 v82, v93, v154
	v_fma_f32 v81, v93, v153, v148
	ds_bpermute_b32 v90, v147, v196
	v_fmac_f32_e32 v82, v94, v155
	v_fmac_f32_e32 v81, v94, v154
	v_fma_f32 v80, v94, v153, v148
	ds_bpermute_b32 v94, v147, v192
	v_fma_f32 v106, v66, v150, v149
	s_waitcnt lgkmcnt(5)
	v_fmac_f32_e32 v84, v155, v105
	v_fma_f32 v105, v65, v150, v149
	v_fmac_f32_e32 v106, v67, v151
	v_fmac_f32_e32 v105, v66, v151
	s_waitcnt lgkmcnt(4)
	v_fmac_f32_e32 v106, v152, v91
	v_fma_f32 v91, v68, v150, v149
	v_cndmask_b32_e64 v99, 0, v208, s[2:3]
	v_fmac_f32_e32 v105, v67, v152
	s_waitcnt lgkmcnt(3)
	v_fma_f32 v67, v150, v92, v149
	v_fmac_f32_e32 v91, v69, v151
	v_fma_f32 v92, v69, v150, v149
	v_fmac_f32_e32 v87, v89, v155
	s_waitcnt lgkmcnt(2)
	v_cndmask_b32_e32 v89, v99, v107, vcc
	ds_bpermute_b32 v99, v147, v190
	s_waitcnt lgkmcnt(2)
	v_cndmask_b32_e32 v90, v90, v205, vcc
	v_fmac_f32_e32 v91, v70, v152
	v_fmac_f32_e32 v92, v70, v151
	v_fma_f32 v70, v70, v150, v149
	v_fma_f32 v90, v150, v90, v149
	v_fmac_f32_e32 v92, v71, v152
	v_fmac_f32_e32 v70, v71, v151
	s_waitcnt lgkmcnt(1)
	v_fma_f32 v71, v150, v94, v149
	v_fmac_f32_e32 v90, v64, v151
	v_fma_f32 v104, v64, v150, v149
	v_fmac_f32_e32 v71, v72, v151
	v_fma_f32 v72, v72, v150, v149
	v_mul_f32_e32 v64, 0x3d372713, v100
	v_fmac_f32_e32 v71, v73, v152
	v_fmac_f32_e32 v72, v73, v151
	v_fma_f32 v73, v73, v150, v149
	v_mul_f32_e32 v64, v100, v64
	v_fmac_f32_e32 v72, v74, v152
	v_fmac_f32_e32 v73, v74, v151
	v_fma_f32 v74, v74, v150, v149
	v_fma_f32 v64, v100, v64, v100
	v_fmac_f32_e32 v104, v65, v151
	v_fmac_f32_e32 v73, v75, v152
	v_fmac_f32_e32 v74, v75, v151
	s_waitcnt lgkmcnt(0)
	v_fma_f32 v75, v150, v99, v149
	v_mul_f32_e32 v64, 0xbfcc422a, v64
	v_fmac_f32_e32 v104, v66, v152
	v_fmac_f32_e32 v75, v76, v151
	v_fma_f32 v66, v76, v150, v149
	v_mul_f32_e32 v64, 0x3fb8aa3b, v64
	ds_bpermute_b32 v103, v147, v201
	v_fmac_f32_e32 v90, v65, v152
	v_fmac_f32_e32 v67, v68, v151
	v_fmac_f32_e32 v75, v77, v152
	v_fmac_f32_e32 v66, v77, v151
	v_fma_f32 v65, v77, v150, v149
	v_exp_f32_e32 v68, v64
	v_mul_f32_e32 v77, 0x3d372713, v108
	v_mul_f32_e32 v77, v108, v77
	v_fma_f32 v77, v108, v77, v108
	v_mul_f32_e32 v77, 0xbfcc422a, v77
	v_add_f32_e32 v68, 1.0, v68
	v_mul_f32_e32 v77, 0x3fb8aa3b, v77
	s_waitcnt lgkmcnt(0)
	v_fmac_f32_e32 v86, v155, v103
	ds_bpermute_b32 v103, v147, v189
	v_rcp_f32_e32 v68, v68
	v_exp_f32_e32 v77, v77
	v_fmac_f32_e32 v80, v95, v154
	v_fmac_f32_e32 v80, v155, v89
	v_cndmask_b32_e64 v89, 0, v206, s[2:3]
	v_fma_f32 v64, v78, v150, v149
	v_mul_f32_e32 v68, v100, v68
	v_add_f32_e32 v77, 1.0, v77
	v_fmac_f32_e32 v67, v69, v152
	s_waitcnt lgkmcnt(0)
	v_cndmask_b32_e32 v69, v89, v103, vcc
	v_fmac_f32_e32 v64, v79, v151
	v_mul_f32_e32 v68, v90, v68
	v_rcp_f32_e32 v77, v77
	v_fmac_f32_e32 v64, v152, v69
	v_bfe_u32 v76, v68, 16, 1
	v_add3_u32 v76, v68, v76, s89
	s_add_u32 s20, s18, 0x2c000
	s_addc_u32 s21, s19, 0
	global_store_short_d16_hi v98, v76, s[20:21]
	v_mul_f32_e32 v69, v108, v77
	v_mul_f32_e32 v77, 0x3d372713, v109
	v_mul_f32_e32 v77, v109, v77
	v_fma_f32 v77, v109, v77, v109
	v_mul_f32_e32 v77, 0xbfcc422a, v77
	v_mul_f32_e32 v77, 0x3fb8aa3b, v77
	v_exp_f32_e32 v77, v77
	v_mul_f32_e32 v69, v104, v69
	v_bfe_u32 v76, v69, 16, 1
	v_add_f32_e32 v77, 1.0, v77
	v_rcp_f32_e32 v77, v77
	v_add3_u32 v76, v69, v76, s89
	s_add_u32 s20, s18, 0x2d600
	s_addc_u32 s21, s19, 0
	global_store_short_d16_hi v98, v76, s[20:21]
	v_mul_f32_e32 v69, v109, v77
	v_mul_f32_e32 v77, 0x3d372713, v110
	v_mul_f32_e32 v77, v110, v77
	v_fma_f32 v77, v110, v77, v110
	v_mul_f32_e32 v77, 0xbfcc422a, v77
	v_mul_f32_e32 v77, 0x3fb8aa3b, v77
	v_exp_f32_e32 v77, v77
	v_mul_f32_e32 v69, v105, v69
	v_bfe_u32 v76, v69, 16, 1
	v_add_f32_e32 v77, 1.0, v77
	v_rcp_f32_e32 v77, v77
	v_add3_u32 v76, v69, v76, s89
	v_fmac_f32_e32 v83, v93, v155
	v_fmac_f32_e32 v81, v95, v155
	ds_bpermute_b32 v93, v147, v193
	ds_bpermute_b32 v95, v147, v191
	s_add_u32 s20, s18, 0x2ec00
	s_addc_u32 s21, s19, 0
	global_store_short_d16_hi v98, v76, s[20:21]
	v_mul_f32_e32 v69, v110, v77
	v_mul_f32_e32 v69, v106, v69
	v_bfe_u32 v76, v69, 16, 1
	v_add3_u32 v76, v69, v76, s89
	v_fmac_f32_e32 v65, v78, v151
	s_waitcnt lgkmcnt(1)
	v_fmac_f32_e32 v70, v152, v93
	s_waitcnt lgkmcnt(0)
	v_fmac_f32_e32 v74, v152, v95
	v_fmac_f32_e32 v66, v78, v152
	v_fmac_f32_e32 v65, v79, v152
	s_add_u32 s20, s18, 0x30200
	s_addc_u32 s21, s19, 0
	global_store_short_d16_hi v98, v76, s[20:21]
	v_mul_f32_e32 v69, 0x3d372713, v101
	v_mul_f32_e32 v69, v101, v69
	v_fma_f32 v69, v101, v69, v101
	v_mul_f32_e32 v69, 0xbfcc422a, v69
	v_mul_f32_e32 v69, 0x3fb8aa3b, v69
	v_exp_f32_e32 v69, v69
	s_nop 0
	v_add_f32_e32 v69, 1.0, v69
	v_rcp_f32_e32 v69, v69
	s_nop 0
	v_mul_f32_e32 v69, v101, v69
	v_mul_f32_e32 v67, v67, v69
	v_bfe_u32 v69, v67, 16, 1
	v_add3_u32 v67, v67, v69, s89
	s_add_u32 s20, s18, 0x37000
	s_addc_u32 s21, s19, 0
	global_store_short_d16_hi v98, v67, s[20:21]
	v_mul_f32_e32 v68, 0x3d372713, v102
	v_mul_f32_e32 v68, v102, v68
	v_fma_f32 v68, v102, v68, v102
	v_mul_f32_e32 v68, 0xbfcc422a, v68
	v_mul_f32_e32 v68, 0x3fb8aa3b, v68
	v_exp_f32_e32 v68, v68
	s_nop 0
	v_add_f32_e32 v68, 1.0, v68
	v_rcp_f32_e32 v68, v68
	s_nop 0
	v_mul_f32_e32 v68, v102, v68
	v_mul_f32_e32 v68, v91, v68
	v_bfe_u32 v69, v68, 16, 1
	v_add3_u32 v76, v68, v69, s89
	s_add_u32 s20, s18, 0x38600
	s_addc_u32 s21, s19, 0
	global_store_short_d16_hi v98, v76, s[20:21]
	v_mul_f32_e32 v68, 0x3d372713, v111
	v_mul_f32_e32 v68, v111, v68
	v_fma_f32 v68, v111, v68, v111
	v_mul_f32_e32 v68, 0xbfcc422a, v68
	v_mul_f32_e32 v68, 0x3fb8aa3b, v68
	v_exp_f32_e32 v68, v68
	s_nop 0
	v_add_f32_e32 v68, 1.0, v68
	v_rcp_f32_e32 v68, v68
	s_nop 0
	v_mul_f32_e32 v68, v111, v68
	v_mul_f32_e32 v68, v92, v68
	v_bfe_u32 v69, v68, 16, 1
	v_add3_u32 v76, v68, v69, s89
	s_add_u32 s20, s18, 0x39c00
	s_addc_u32 s21, s19, 0
	global_store_short_d16_hi v98, v76, s[20:21]
	v_mul_f32_e32 v68, 0x3d372713, v86
	v_mul_f32_e32 v68, v86, v68
	v_fma_f32 v68, v86, v68, v86
	v_mul_f32_e32 v68, 0xbfcc422a, v68
	v_mul_f32_e32 v68, 0x3fb8aa3b, v68
	v_exp_f32_e32 v68, v68
	s_nop 0
	v_add_f32_e32 v68, 1.0, v68
	v_rcp_f32_e32 v68, v68
	s_nop 0
	v_mul_f32_e32 v68, v86, v68
	v_mul_f32_e32 v68, v70, v68
	v_bfe_u32 v69, v68, 16, 1
	v_add3_u32 v70, v68, v69, s89
	s_add_u32 s20, s18, 0x3b200
	s_addc_u32 s21, s19, 0
	global_store_short_d16_hi v98, v70, s[20:21]
	v_mul_f32_e32 v68, 0x3d372713, v87
	v_mul_f32_e32 v68, v87, v68
	v_fma_f32 v68, v87, v68, v87
	v_mul_f32_e32 v68, 0xbfcc422a, v68
	v_mul_f32_e32 v68, 0x3fb8aa3b, v68
	v_exp_f32_e32 v68, v68
	s_nop 0
	v_add_f32_e32 v68, 1.0, v68
	v_rcp_f32_e32 v68, v68
	s_nop 0
	v_mul_f32_e32 v68, v87, v68
	v_mul_f32_e32 v68, v71, v68
	v_bfe_u32 v69, v68, 16, 1
	v_add3_u32 v70, v68, v69, s89
	s_add_u32 s20, s18, 0x42000
	s_addc_u32 s21, s19, 0
	global_store_short_d16_hi v98, v70, s[20:21]
	v_mul_f32_e32 v68, 0x3d372713, v88
	v_mul_f32_e32 v68, v88, v68
	v_fma_f32 v68, v88, v68, v88
	v_mul_f32_e32 v68, 0xbfcc422a, v68
	v_mul_f32_e32 v68, 0x3fb8aa3b, v68
	v_exp_f32_e32 v68, v68
	s_nop 0
	v_add_f32_e32 v68, 1.0, v68
	v_rcp_f32_e32 v68, v68
	s_nop 0
	v_mul_f32_e32 v68, v88, v68
	v_mul_f32_e32 v68, v72, v68
	v_bfe_u32 v69, v68, 16, 1
	v_add3_u32 v70, v68, v69, s89
	s_add_u32 s20, s18, 0x43600
	s_addc_u32 s21, s19, 0
	global_store_short_d16_hi v98, v70, s[20:21]
	v_mul_f32_e32 v68, 0x3d372713, v85
	v_mul_f32_e32 v68, v85, v68
	v_fma_f32 v68, v85, v68, v85
	v_mul_f32_e32 v68, 0xbfcc422a, v68
	v_mul_f32_e32 v68, 0x3fb8aa3b, v68
	v_exp_f32_e32 v68, v68
	s_nop 0
	v_add_f32_e32 v68, 1.0, v68
	v_rcp_f32_e32 v68, v68
	s_nop 0
	v_mul_f32_e32 v68, v85, v68
	v_mul_f32_e32 v68, v73, v68
	v_bfe_u32 v69, v68, 16, 1
	v_add3_u32 v70, v68, v69, s89
	s_add_u32 s20, s18, 0x44c00
	s_addc_u32 s21, s19, 0
	global_store_short_d16_hi v98, v70, s[20:21]
	v_mul_f32_e32 v68, 0x3d372713, v84
	v_mul_f32_e32 v68, v84, v68
	v_fma_f32 v68, v84, v68, v84
	v_mul_f32_e32 v68, 0xbfcc422a, v68
	v_mul_f32_e32 v68, 0x3fb8aa3b, v68
	v_exp_f32_e32 v68, v68
	s_nop 0
	v_add_f32_e32 v68, 1.0, v68
	v_rcp_f32_e32 v68, v68
	s_nop 0
	v_mul_f32_e32 v68, v84, v68
	v_mul_f32_e32 v68, v74, v68
	v_bfe_u32 v69, v68, 16, 1
	v_add3_u32 v70, v68, v69, s89
	s_add_u32 s20, s18, 0x46200
	s_addc_u32 s21, s19, 0
	global_store_short_d16_hi v98, v70, s[20:21]
	v_mul_f32_e32 v68, 0x3d372713, v83
	v_mul_f32_e32 v68, v83, v68
	v_fma_f32 v68, v83, v68, v83
	v_mul_f32_e32 v68, 0xbfcc422a, v68
	v_mul_f32_e32 v68, 0x3fb8aa3b, v68
	v_exp_f32_e32 v68, v68
	s_nop 0
	v_add_f32_e32 v68, 1.0, v68
	v_rcp_f32_e32 v68, v68
	s_nop 0
	v_mul_f32_e32 v68, v83, v68
	v_mul_f32_e32 v68, v75, v68
	v_bfe_u32 v69, v68, 16, 1
	v_add3_u32 v70, v68, v69, s89
	s_add_u32 s20, s18, 0x4d000
	s_addc_u32 s21, s19, 0
	global_store_short_d16_hi v98, v70, s[20:21]
	v_mul_f32_e32 v68, 0x3d372713, v82
	v_mul_f32_e32 v68, v82, v68
	v_fma_f32 v68, v82, v68, v82
	v_mul_f32_e32 v68, 0xbfcc422a, v68
	v_mul_f32_e32 v68, 0x3fb8aa3b, v68
	v_exp_f32_e32 v68, v68
	s_nop 0
	v_add_f32_e32 v68, 1.0, v68
	v_rcp_f32_e32 v68, v68
	s_nop 0
	v_mul_f32_e32 v68, v82, v68
	v_mul_f32_e32 v66, v66, v68
	v_bfe_u32 v68, v66, 16, 1
	v_add3_u32 v68, v66, v68, s89
	s_add_u32 s20, s18, 0x4e600
	s_addc_u32 s21, s19, 0
	global_store_short_d16_hi v98, v68, s[20:21]
	v_mul_f32_e32 v67, 0x3d372713, v81
	v_mul_f32_e32 v67, v81, v67
	v_fma_f32 v67, v81, v67, v81
	v_mul_f32_e32 v67, 0xbfcc422a, v67
	v_mul_f32_e32 v67, 0x3fb8aa3b, v67
	v_exp_f32_e32 v67, v67
	s_nop 0
	v_add_f32_e32 v67, 1.0, v67
	v_rcp_f32_e32 v67, v67
	s_nop 0
	v_mul_f32_e32 v67, v81, v67
	v_mul_f32_e32 v65, v65, v67
	v_bfe_u32 v67, v65, 16, 1
	v_add3_u32 v65, v65, v67, s89
	s_add_u32 s20, s18, 0x4fc00
	s_addc_u32 s21, s19, 0
	global_store_short_d16_hi v98, v65, s[20:21]
	v_mul_f32_e32 v66, 0x3d372713, v80
	v_mul_f32_e32 v66, v80, v66
	v_fma_f32 v66, v80, v66, v80
	v_mul_f32_e32 v66, 0xbfcc422a, v66
	v_mul_f32_e32 v66, 0x3fb8aa3b, v66
	v_exp_f32_e32 v66, v66
	s_nop 0
	v_add_f32_e32 v66, 1.0, v66
	v_rcp_f32_e32 v66, v66
	s_nop 0
	v_mul_f32_e32 v66, v80, v66
	v_mul_f32_e32 v64, v64, v66
	v_bfe_u32 v66, v64, 16, 1
	v_add3_u32 v66, v64, v66, s89
	s_add_u32 s20, s18, 0x51200
	s_addc_u32 s21, s19, 0
	global_store_short_d16_hi v98, v66, s[20:21]
	ds_bpermute_b32 v66, v147, v184
	ds_bpermute_b32 v67, v147, v182
	ds_bpermute_b32 v65, v147, v185
	ds_bpermute_b32 v69, v147, v180
	v_fma_f32 v74, v50, v153, v148
	ds_bpermute_b32 v71, v147, v178
	v_fmac_f32_e32 v74, v51, v154
	s_waitcnt lgkmcnt(4)
	v_fmac_f32_e32 v74, v155, v66
	s_waitcnt lgkmcnt(3)
	v_fma_f32 v66, v153, v67, v148
	v_fma_f32 v67, v52, v153, v148
	v_fmac_f32_e32 v66, v52, v154
	v_fmac_f32_e32 v67, v53, v154
	v_fma_f32 v75, v53, v153, v148
	v_cndmask_b32_e64 v64, 0, v188, s[2:3]
	v_fma_f32 v73, v49, v153, v148
	v_fmac_f32_e32 v66, v53, v155
	v_fmac_f32_e32 v67, v54, v155
	v_fmac_f32_e32 v75, v54, v154
	v_fma_f32 v54, v54, v153, v148
	v_fma_f32 v53, v57, v153, v148
	ds_bpermute_b32 v70, v147, v179
	s_waitcnt lgkmcnt(3)
	v_cndmask_b32_e32 v64, v65, v64, vcc
	v_fma_f32 v65, v48, v153, v148
	v_fmac_f32_e32 v73, v50, v154
	v_fmac_f32_e32 v75, v55, v155
	v_fmac_f32_e32 v54, v55, v154
	s_waitcnt lgkmcnt(2)
	v_fma_f32 v55, v153, v69, v148
	v_fmac_f32_e32 v53, v58, v154
	v_fma_f32 v52, v58, v153, v148
	ds_bpermute_b32 v72, v147, v177
	v_fma_f32 v64, v153, v64, v148
	v_fmac_f32_e32 v65, v49, v154
	v_fmac_f32_e32 v73, v51, v155
	v_fmac_f32_e32 v55, v56, v154
	v_fma_f32 v56, v56, v153, v148
	v_fmac_f32_e32 v53, v59, v155
	v_fmac_f32_e32 v52, v59, v154
	s_waitcnt lgkmcnt(2)
	v_fma_f32 v51, v153, v71, v148
	ds_bpermute_b32 v59, v147, v175
	v_fmac_f32_e32 v64, v48, v154
	v_fmac_f32_e32 v65, v50, v155
	v_fmac_f32_e32 v56, v57, v154
	v_fmac_f32_e32 v51, v60, v154
	v_fma_f32 v50, v60, v153, v148
	ds_bpermute_b32 v60, v147, v174
	ds_bpermute_b32 v68, v147, v181
	v_fmac_f32_e32 v64, v49, v155
	v_fmac_f32_e32 v56, v58, v155
	v_fmac_f32_e32 v50, v61, v154
	v_fma_f32 v49, v61, v153, v148
	ds_bpermute_b32 v58, v147, v176
	v_fmac_f32_e32 v50, v62, v155
	v_fmac_f32_e32 v49, v62, v154
	v_fma_f32 v48, v62, v153, v148
	ds_bpermute_b32 v62, v147, v172
	v_fma_f32 v71, v34, v150, v149
	s_waitcnt lgkmcnt(6)
	v_fmac_f32_e32 v52, v155, v70
	v_fma_f32 v70, v33, v150, v149
	v_fmac_f32_e32 v71, v35, v151
	v_fmac_f32_e32 v55, v57, v155
	s_waitcnt lgkmcnt(5)
	v_cndmask_b32_e32 v57, v187, v72, vcc
	v_fmac_f32_e32 v48, v63, v154
	v_fmac_f32_e32 v70, v34, v151
	s_waitcnt lgkmcnt(4)
	v_fmac_f32_e32 v71, v152, v59
	v_fma_f32 v59, v36, v150, v149
	v_fmac_f32_e32 v48, v155, v57
	v_cndmask_b32_e64 v57, 0, v186, s[2:3]
	v_fmac_f32_e32 v70, v35, v152
	s_waitcnt lgkmcnt(3)
	v_fma_f32 v35, v150, v60, v149
	v_fmac_f32_e32 v59, v37, v151
	v_fma_f32 v60, v37, v150, v149
	s_waitcnt lgkmcnt(2)
	v_fmac_f32_e32 v54, v155, v68
	ds_bpermute_b32 v68, v147, v170
	s_waitcnt lgkmcnt(2)
	v_cndmask_b32_e32 v57, v58, v57, vcc
	v_fmac_f32_e32 v59, v38, v152
	v_fmac_f32_e32 v60, v38, v151
	v_fma_f32 v38, v38, v150, v149
	v_fma_f32 v57, v150, v57, v149
	v_fmac_f32_e32 v60, v39, v152
	v_fmac_f32_e32 v38, v39, v151
	s_waitcnt lgkmcnt(1)
	v_fma_f32 v39, v150, v62, v149
	v_fmac_f32_e32 v57, v32, v151
	v_fma_f32 v58, v32, v150, v149
	v_fmac_f32_e32 v39, v40, v151
	v_fma_f32 v40, v40, v150, v149
	v_mul_f32_e32 v32, 0x3d372713, v64
	v_fmac_f32_e32 v39, v41, v152
	v_fmac_f32_e32 v40, v41, v151
	v_fma_f32 v41, v41, v150, v149
	v_mul_f32_e32 v32, v64, v32
	v_fmac_f32_e32 v40, v42, v152
	v_fmac_f32_e32 v41, v42, v151
	v_fma_f32 v42, v42, v150, v149
	v_fma_f32 v32, v64, v32, v64
	v_fmac_f32_e32 v58, v33, v151
	v_fmac_f32_e32 v41, v43, v152
	v_fmac_f32_e32 v42, v43, v151
	s_waitcnt lgkmcnt(0)
	v_fma_f32 v43, v150, v68, v149
	v_mul_f32_e32 v32, 0xbfcc422a, v32
	v_fmac_f32_e32 v58, v34, v152
	v_fmac_f32_e32 v43, v44, v151
	v_fma_f32 v34, v44, v150, v149
	v_mul_f32_e32 v32, 0x3fb8aa3b, v32
	v_fmac_f32_e32 v57, v33, v152
	v_fmac_f32_e32 v35, v36, v151
	v_fmac_f32_e32 v43, v45, v152
	v_fmac_f32_e32 v34, v45, v151
	v_fma_f32 v33, v45, v150, v149
	v_exp_f32_e32 v36, v32
	v_mul_f32_e32 v45, 0x3d372713, v65
	v_mul_f32_e32 v45, v65, v45
	v_fma_f32 v45, v65, v45, v65
	v_mul_f32_e32 v45, 0xbfcc422a, v45
	v_add_f32_e32 v36, 1.0, v36
	v_mul_f32_e32 v45, 0x3fb8aa3b, v45
	ds_bpermute_b32 v69, v147, v169
	v_rcp_f32_e32 v36, v36
	v_exp_f32_e32 v45, v45
	v_fma_f32 v32, v46, v150, v149
	v_fmac_f32_e32 v35, v37, v152
	v_mul_f32_e32 v36, v64, v36
	v_add_f32_e32 v45, 1.0, v45
	s_waitcnt lgkmcnt(0)
	v_cndmask_b32_e32 v37, v183, v69, vcc
	v_fmac_f32_e32 v32, v47, v151
	v_mul_f32_e32 v36, v57, v36
	v_rcp_f32_e32 v45, v45
	v_fmac_f32_e32 v32, v152, v37
	v_bfe_u32 v44, v36, 16, 1
	v_add3_u32 v44, v36, v44, s89
	s_add_u32 s20, s18, 0x58000
	s_addc_u32 s21, s19, 0
	global_store_short_d16_hi v98, v44, s[20:21]
	v_mul_f32_e32 v37, v65, v45
	v_mul_f32_e32 v45, 0x3d372713, v73
	v_mul_f32_e32 v45, v73, v45
	v_fma_f32 v45, v73, v45, v73
	v_mul_f32_e32 v45, 0xbfcc422a, v45
	v_mul_f32_e32 v45, 0x3fb8aa3b, v45
	v_exp_f32_e32 v45, v45
	v_mul_f32_e32 v37, v58, v37
	v_bfe_u32 v44, v37, 16, 1
	v_add_f32_e32 v45, 1.0, v45
	v_rcp_f32_e32 v45, v45
	v_add3_u32 v44, v37, v44, s89
	s_add_u32 s20, s18, 0x59600
	s_addc_u32 s21, s19, 0
	global_store_short_d16_hi v98, v44, s[20:21]
	v_mul_f32_e32 v37, v73, v45
	v_mul_f32_e32 v45, 0x3d372713, v74
	v_mul_f32_e32 v45, v74, v45
	v_fma_f32 v45, v74, v45, v74
	v_mul_f32_e32 v45, 0xbfcc422a, v45
	v_mul_f32_e32 v45, 0x3fb8aa3b, v45
	v_exp_f32_e32 v45, v45
	v_mul_f32_e32 v37, v70, v37
	v_bfe_u32 v44, v37, 16, 1
	v_add_f32_e32 v45, 1.0, v45
	v_rcp_f32_e32 v45, v45
	v_add3_u32 v44, v37, v44, s89
	v_fmac_f32_e32 v51, v61, v155
	v_fmac_f32_e32 v49, v63, v155
	ds_bpermute_b32 v61, v147, v173
	ds_bpermute_b32 v63, v147, v171
	s_add_u32 s20, s18, 0x5ac00
	s_addc_u32 s21, s19, 0
	global_store_short_d16_hi v98, v44, s[20:21]
	v_mul_f32_e32 v37, v74, v45
	v_mul_f32_e32 v37, v71, v37
	v_bfe_u32 v44, v37, 16, 1
	v_add3_u32 v44, v37, v44, s89
	v_fmac_f32_e32 v33, v46, v151
	s_waitcnt lgkmcnt(1)
	v_fmac_f32_e32 v38, v152, v61
	s_waitcnt lgkmcnt(0)
	v_fmac_f32_e32 v42, v152, v63
	v_fmac_f32_e32 v34, v46, v152
	v_fmac_f32_e32 v33, v47, v152
	s_add_u32 s20, s18, 0x5c200
	s_addc_u32 s21, s19, 0
	global_store_short_d16_hi v98, v44, s[20:21]
	v_mul_f32_e32 v37, 0x3d372713, v66
	v_mul_f32_e32 v37, v66, v37
	v_fma_f32 v37, v66, v37, v66
	v_mul_f32_e32 v37, 0xbfcc422a, v37
	v_mul_f32_e32 v37, 0x3fb8aa3b, v37
	v_exp_f32_e32 v37, v37
	s_nop 0
	v_add_f32_e32 v37, 1.0, v37
	v_rcp_f32_e32 v37, v37
	s_nop 0
	v_mul_f32_e32 v37, v66, v37
	v_mul_f32_e32 v35, v35, v37
	v_bfe_u32 v37, v35, 16, 1
	v_add3_u32 v35, v35, v37, s89
	s_add_u32 s20, s18, 0x63000
	s_addc_u32 s21, s19, 0
	global_store_short_d16_hi v98, v35, s[20:21]
	v_mul_f32_e32 v36, 0x3d372713, v67
	v_mul_f32_e32 v36, v67, v36
	v_fma_f32 v36, v67, v36, v67
	v_mul_f32_e32 v36, 0xbfcc422a, v36
	v_mul_f32_e32 v36, 0x3fb8aa3b, v36
	v_exp_f32_e32 v36, v36
	s_nop 0
	v_add_f32_e32 v36, 1.0, v36
	v_rcp_f32_e32 v36, v36
	s_nop 0
	v_mul_f32_e32 v36, v67, v36
	v_mul_f32_e32 v36, v59, v36
	v_bfe_u32 v37, v36, 16, 1
	v_add3_u32 v44, v36, v37, s89
	s_add_u32 s20, s18, 0x64600
	s_addc_u32 s21, s19, 0
	global_store_short_d16_hi v98, v44, s[20:21]
	v_mul_f32_e32 v36, 0x3d372713, v75
	v_mul_f32_e32 v36, v75, v36
	v_fma_f32 v36, v75, v36, v75
	v_mul_f32_e32 v36, 0xbfcc422a, v36
	v_mul_f32_e32 v36, 0x3fb8aa3b, v36
	v_exp_f32_e32 v36, v36
	s_nop 0
	v_add_f32_e32 v36, 1.0, v36
	v_rcp_f32_e32 v36, v36
	s_nop 0
	v_mul_f32_e32 v36, v75, v36
	v_mul_f32_e32 v36, v60, v36
	v_bfe_u32 v37, v36, 16, 1
	v_add3_u32 v44, v36, v37, s89
	s_add_u32 s20, s18, 0x65c00
	s_addc_u32 s21, s19, 0
	global_store_short_d16_hi v98, v44, s[20:21]
	v_mul_f32_e32 v36, 0x3d372713, v54
	v_mul_f32_e32 v36, v54, v36
	v_fma_f32 v36, v54, v36, v54
	v_mul_f32_e32 v36, 0xbfcc422a, v36
	v_mul_f32_e32 v36, 0x3fb8aa3b, v36
	v_exp_f32_e32 v36, v36
	s_nop 0
	v_add_f32_e32 v36, 1.0, v36
	v_rcp_f32_e32 v36, v36
	s_nop 0
	v_mul_f32_e32 v36, v54, v36
	v_mul_f32_e32 v36, v38, v36
	v_bfe_u32 v37, v36, 16, 1
	v_add3_u32 v38, v36, v37, s89
	s_add_u32 s20, s18, 0x67200
	s_addc_u32 s21, s19, 0
	global_store_short_d16_hi v98, v38, s[20:21]
	v_mul_f32_e32 v36, 0x3d372713, v55
	v_mul_f32_e32 v36, v55, v36
	v_fma_f32 v36, v55, v36, v55
	v_mul_f32_e32 v36, 0xbfcc422a, v36
	v_mul_f32_e32 v36, 0x3fb8aa3b, v36
	v_exp_f32_e32 v36, v36
	s_nop 0
	v_add_f32_e32 v36, 1.0, v36
	v_rcp_f32_e32 v36, v36
	s_nop 0
	v_mul_f32_e32 v36, v55, v36
	v_mul_f32_e32 v36, v39, v36
	v_bfe_u32 v37, v36, 16, 1
	v_add3_u32 v38, v36, v37, s89
	s_add_u32 s20, s18, 0x6e000
	s_addc_u32 s21, s19, 0
	global_store_short_d16_hi v98, v38, s[20:21]
	v_mul_f32_e32 v36, 0x3d372713, v56
	v_mul_f32_e32 v36, v56, v36
	v_fma_f32 v36, v56, v36, v56
	v_mul_f32_e32 v36, 0xbfcc422a, v36
	v_mul_f32_e32 v36, 0x3fb8aa3b, v36
	v_exp_f32_e32 v36, v36
	s_nop 0
	v_add_f32_e32 v36, 1.0, v36
	v_rcp_f32_e32 v36, v36
	s_nop 0
	v_mul_f32_e32 v36, v56, v36
	v_mul_f32_e32 v36, v40, v36
	v_bfe_u32 v37, v36, 16, 1
	v_add3_u32 v38, v36, v37, s89
	s_add_u32 s20, s18, 0x6f600
	s_addc_u32 s21, s19, 0
	global_store_short_d16_hi v98, v38, s[20:21]
	v_mul_f32_e32 v36, 0x3d372713, v53
	v_mul_f32_e32 v36, v53, v36
	v_fma_f32 v36, v53, v36, v53
	v_mul_f32_e32 v36, 0xbfcc422a, v36
	v_mul_f32_e32 v36, 0x3fb8aa3b, v36
	v_exp_f32_e32 v36, v36
	s_nop 0
	v_add_f32_e32 v36, 1.0, v36
	v_rcp_f32_e32 v36, v36
	s_nop 0
	v_mul_f32_e32 v36, v53, v36
	v_mul_f32_e32 v36, v41, v36
	v_bfe_u32 v37, v36, 16, 1
	v_add3_u32 v38, v36, v37, s89
	s_add_u32 s20, s18, 0x70c00
	s_addc_u32 s21, s19, 0
	global_store_short_d16_hi v98, v38, s[20:21]
	v_mul_f32_e32 v36, 0x3d372713, v52
	v_mul_f32_e32 v36, v52, v36
	v_fma_f32 v36, v52, v36, v52
	v_mul_f32_e32 v36, 0xbfcc422a, v36
	v_mul_f32_e32 v36, 0x3fb8aa3b, v36
	v_exp_f32_e32 v36, v36
	s_nop 0
	v_add_f32_e32 v36, 1.0, v36
	v_rcp_f32_e32 v36, v36
	s_nop 0
	v_mul_f32_e32 v36, v52, v36
	v_mul_f32_e32 v36, v42, v36
	v_bfe_u32 v37, v36, 16, 1
	v_add3_u32 v38, v36, v37, s89
	s_add_u32 s20, s18, 0x72200
	s_addc_u32 s21, s19, 0
	global_store_short_d16_hi v98, v38, s[20:21]
	v_mul_f32_e32 v36, 0x3d372713, v51
	v_mul_f32_e32 v36, v51, v36
	v_fma_f32 v36, v51, v36, v51
	v_mul_f32_e32 v36, 0xbfcc422a, v36
	v_mul_f32_e32 v36, 0x3fb8aa3b, v36
	v_exp_f32_e32 v36, v36
	s_nop 0
	v_add_f32_e32 v36, 1.0, v36
	v_rcp_f32_e32 v36, v36
	s_nop 0
	v_mul_f32_e32 v36, v51, v36
	v_mul_f32_e32 v36, v43, v36
	v_bfe_u32 v37, v36, 16, 1
	v_add3_u32 v38, v36, v37, s89
	s_add_u32 s20, s18, 0x79000
	s_addc_u32 s21, s19, 0
	global_store_short_d16_hi v98, v38, s[20:21]
	v_mul_f32_e32 v36, 0x3d372713, v50
	v_mul_f32_e32 v36, v50, v36
	v_fma_f32 v36, v50, v36, v50
	v_mul_f32_e32 v36, 0xbfcc422a, v36
	v_mul_f32_e32 v36, 0x3fb8aa3b, v36
	v_exp_f32_e32 v36, v36
	s_nop 0
	v_add_f32_e32 v36, 1.0, v36
	v_rcp_f32_e32 v36, v36
	s_nop 0
	v_mul_f32_e32 v36, v50, v36
	v_mul_f32_e32 v34, v34, v36
	v_bfe_u32 v36, v34, 16, 1
	v_add3_u32 v36, v34, v36, s89
	s_add_u32 s20, s18, 0x7a600
	s_addc_u32 s21, s19, 0
	global_store_short_d16_hi v98, v36, s[20:21]
	v_mul_f32_e32 v35, 0x3d372713, v49
	v_mul_f32_e32 v35, v49, v35
	v_fma_f32 v35, v49, v35, v49
	v_mul_f32_e32 v35, 0xbfcc422a, v35
	v_mul_f32_e32 v35, 0x3fb8aa3b, v35
	v_exp_f32_e32 v35, v35
	s_nop 0
	v_add_f32_e32 v35, 1.0, v35
	v_rcp_f32_e32 v35, v35
	s_nop 0
	v_mul_f32_e32 v35, v49, v35
	v_mul_f32_e32 v33, v33, v35
	v_bfe_u32 v35, v33, 16, 1
	v_add3_u32 v33, v33, v35, s89
	s_add_u32 s20, s18, 0x7bc00
	s_addc_u32 s21, s19, 0
	global_store_short_d16_hi v98, v33, s[20:21]
	v_mul_f32_e32 v34, 0x3d372713, v48
	v_mul_f32_e32 v34, v48, v34
	v_fma_f32 v34, v48, v34, v48
	v_mul_f32_e32 v34, 0xbfcc422a, v34
	v_mul_f32_e32 v34, 0x3fb8aa3b, v34
	v_exp_f32_e32 v34, v34
	s_nop 0
	v_add_f32_e32 v34, 1.0, v34
	v_rcp_f32_e32 v34, v34
	s_nop 0
	v_mul_f32_e32 v34, v48, v34
	v_mul_f32_e32 v32, v32, v34
	v_bfe_u32 v34, v32, 16, 1
	v_add3_u32 v34, v32, v34, s89
	s_add_u32 s20, s18, 0x7d200
	s_addc_u32 s21, s19, 0
	global_store_short_d16_hi v98, v34, s[20:21]
	ds_bpermute_b32 v33, v147, v164
	ds_bpermute_b32 v34, v147, v163
	v_fma_f32 v42, v18, v153, v148
	ds_bpermute_b32 v36, v147, v161
	v_fmac_f32_e32 v42, v19, v154
	s_waitcnt lgkmcnt(2)
	v_fmac_f32_e32 v42, v155, v33
	s_waitcnt lgkmcnt(1)
	v_fma_f32 v33, v153, v34, v148
	v_fmac_f32_e32 v33, v20, v154
	v_fma_f32 v34, v20, v153, v148
	ds_bpermute_b32 v32, v147, v165
	v_fmac_f32_e32 v33, v21, v155
	v_fmac_f32_e32 v34, v21, v154
	v_fma_f32 v21, v21, v153, v148
	v_fmac_f32_e32 v34, v22, v155
	v_fmac_f32_e32 v21, v22, v154
	v_fma_f32 v22, v22, v153, v148
	ds_bpermute_b32 v38, v147, v159
	v_fma_f32 v41, v17, v153, v148
	v_fmac_f32_e32 v21, v23, v155
	v_fmac_f32_e32 v22, v23, v154
	s_waitcnt lgkmcnt(2)
	v_fma_f32 v23, v153, v36, v148
	v_fmac_f32_e32 v41, v18, v154
	v_fmac_f32_e32 v23, v24, v154
	v_fma_f32 v24, v24, v153, v148
	v_fma_f32 v20, v25, v153, v148
	v_fmac_f32_e32 v41, v19, v155
	v_fmac_f32_e32 v24, v25, v154
	v_fmac_f32_e32 v20, v26, v154
	v_fma_f32 v19, v26, v153, v148
	ds_bpermute_b32 v39, v147, v158
	s_waitcnt lgkmcnt(2)
	v_cndmask_b32_e32 v32, v32, v168, vcc
	v_fma_f32 v40, v16, v153, v148
	v_fmac_f32_e32 v24, v26, v155
	v_fmac_f32_e32 v20, v27, v155
	v_fmac_f32_e32 v19, v27, v154
	ds_bpermute_b32 v26, v147, v156
	ds_bpermute_b32 v27, v147, v145
	v_fma_f32 v32, v153, v32, v148
	v_fmac_f32_e32 v40, v17, v154
	v_fmac_f32_e32 v32, v16, v154
	v_fmac_f32_e32 v40, v18, v155
	s_waitcnt lgkmcnt(3)
	v_fma_f32 v18, v153, v38, v148
	v_fmac_f32_e32 v32, v17, v155
	v_fmac_f32_e32 v18, v28, v154
	v_fma_f32 v17, v28, v153, v148
	v_fma_f32 v38, v2, v150, v149
	ds_bpermute_b32 v37, v147, v160
	v_fmac_f32_e32 v18, v29, v155
	v_fmac_f32_e32 v17, v29, v154
	v_fma_f32 v16, v29, v153, v148
	v_fmac_f32_e32 v148, v30, v153
	ds_bpermute_b32 v29, v147, v141
	v_fmac_f32_e32 v38, v3, v151
	v_fmac_f32_e32 v23, v25, v155
	s_waitcnt lgkmcnt(4)
	v_cndmask_b32_e32 v25, v166, v39, vcc
	v_fmac_f32_e32 v148, v154, v31
	s_waitcnt lgkmcnt(3)
	v_fmac_f32_e32 v38, v152, v26
	s_waitcnt lgkmcnt(2)
	v_fma_f32 v26, v150, v27, v149
	v_fmac_f32_e32 v148, v155, v25
	ds_bpermute_b32 v25, v147, v157
	v_fmac_f32_e32 v26, v4, v151
	v_fma_f32 v4, v4, v150, v149
	v_fmac_f32_e32 v16, v30, v154
	v_fmac_f32_e32 v26, v5, v152
	v_fmac_f32_e32 v4, v5, v151
	v_fma_f32 v5, v5, v150, v149
	v_fmac_f32_e32 v16, v155, v31
	ds_bpermute_b32 v31, v147, v135
	v_fma_f32 v36, v0, v150, v149
	v_fmac_f32_e32 v4, v6, v152
	v_fmac_f32_e32 v5, v6, v151
	v_fma_f32 v6, v6, v150, v149
	s_waitcnt lgkmcnt(3)
	v_fmac_f32_e32 v19, v155, v37
	v_fmac_f32_e32 v36, v1, v151
	v_fma_f32 v37, v1, v150, v149
	v_fmac_f32_e32 v5, v7, v152
	v_fmac_f32_e32 v6, v7, v151
	s_waitcnt lgkmcnt(2)
	v_fma_f32 v7, v150, v29, v149
	v_fmac_f32_e32 v36, v2, v152
	v_fmac_f32_e32 v37, v2, v151
	v_fmac_f32_e32 v7, v8, v151
	v_fma_f32 v8, v8, v150, v149
	v_mul_f32_e32 v2, 0x3d372713, v32
	s_waitcnt lgkmcnt(1)
	v_cndmask_b32_e32 v25, v25, v167, vcc
	v_fmac_f32_e32 v7, v9, v152
	v_fmac_f32_e32 v8, v9, v151
	v_fma_f32 v9, v9, v150, v149
	v_mul_f32_e32 v2, v32, v2
	v_fma_f32 v25, v150, v25, v149
	v_fmac_f32_e32 v8, v10, v152
	v_fmac_f32_e32 v9, v10, v151
	v_fma_f32 v10, v10, v150, v149
	v_fma_f32 v2, v32, v2, v32
	v_fmac_f32_e32 v25, v0, v151
	v_fmac_f32_e32 v9, v11, v152
	v_fmac_f32_e32 v10, v11, v151
	s_waitcnt lgkmcnt(0)
	v_fma_f32 v11, v150, v31, v149
	v_mul_f32_e32 v2, 0xbfcc422a, v2
	v_fmac_f32_e32 v25, v1, v152
	v_fmac_f32_e32 v11, v12, v151
	v_fma_f32 v1, v12, v150, v149
	v_mul_f32_e32 v2, 0x3fb8aa3b, v2
	ds_bpermute_b32 v35, v147, v162
	v_fmac_f32_e32 v11, v13, v152
	v_fmac_f32_e32 v1, v13, v151
	v_fma_f32 v0, v13, v150, v149
	v_exp_f32_e32 v2, v2
	v_mul_f32_e32 v13, 0x3d372713, v40
	v_mul_f32_e32 v13, v40, v13
	v_fma_f32 v13, v40, v13, v40
	v_mul_f32_e32 v13, 0xbfcc422a, v13
	v_add_f32_e32 v2, 1.0, v2
	v_mul_f32_e32 v13, 0x3fb8aa3b, v13
	s_waitcnt lgkmcnt(0)
	v_fmac_f32_e32 v22, v155, v35
	ds_bpermute_b32 v35, v147, v133
	v_rcp_f32_e32 v2, v2
	v_exp_f32_e32 v13, v13
	v_fmac_f32_e32 v149, v14, v150
	v_fmac_f32_e32 v37, v3, v152
	v_mul_f32_e32 v2, v32, v2
	v_add_f32_e32 v13, 1.0, v13
	s_waitcnt lgkmcnt(0)
	v_cndmask_b32_e32 v3, v139, v35, vcc
	v_fmac_f32_e32 v149, v15, v151
	v_mul_f32_e32 v2, v25, v2
	v_rcp_f32_e32 v13, v13
	v_fmac_f32_e32 v149, v152, v3
	v_bfe_u32 v12, v2, 16, 1
	v_add3_u32 v12, v2, v12, s89
	s_add_u32 s20, s18, 0x84000
	s_addc_u32 s21, s19, 0
	global_store_short_d16_hi v98, v12, s[20:21]
	v_mul_f32_e32 v3, v40, v13
	v_mul_f32_e32 v13, 0x3d372713, v41
	v_mul_f32_e32 v13, v41, v13
	v_fma_f32 v13, v41, v13, v41
	v_mul_f32_e32 v13, 0xbfcc422a, v13
	v_mul_f32_e32 v13, 0x3fb8aa3b, v13
	v_exp_f32_e32 v13, v13
	v_mul_f32_e32 v3, v36, v3
	v_bfe_u32 v12, v3, 16, 1
	v_add_f32_e32 v13, 1.0, v13
	v_rcp_f32_e32 v13, v13
	v_add3_u32 v12, v3, v12, s89
	s_add_u32 s20, s18, 0x85600
	s_addc_u32 s21, s19, 0
	global_store_short_d16_hi v98, v12, s[20:21]
	v_mul_f32_e32 v3, v41, v13
	v_mul_f32_e32 v13, 0x3d372713, v42
	v_mul_f32_e32 v13, v42, v13
	v_fma_f32 v13, v42, v13, v42
	v_mul_f32_e32 v13, 0xbfcc422a, v13
	v_mul_f32_e32 v13, 0x3fb8aa3b, v13
	v_exp_f32_e32 v13, v13
	v_mul_f32_e32 v3, v37, v3
	v_bfe_u32 v12, v3, 16, 1
	v_add_f32_e32 v13, 1.0, v13
	v_rcp_f32_e32 v13, v13
	v_add3_u32 v12, v3, v12, s89
	v_fmac_f32_e32 v17, v30, v155
	ds_bpermute_b32 v28, v147, v143
	ds_bpermute_b32 v30, v147, v137
	s_add_u32 s20, s18, 0x86c00
	s_addc_u32 s21, s19, 0
	global_store_short_d16_hi v98, v12, s[20:21]
	v_mul_f32_e32 v3, v42, v13
	v_mul_f32_e32 v3, v38, v3
	v_bfe_u32 v12, v3, 16, 1
	v_add3_u32 v12, v3, v12, s89
	v_fmac_f32_e32 v0, v14, v151
	s_waitcnt lgkmcnt(1)
	v_fmac_f32_e32 v6, v152, v28
	s_waitcnt lgkmcnt(0)
	v_fmac_f32_e32 v10, v152, v30
	v_fmac_f32_e32 v1, v14, v152
	v_fmac_f32_e32 v0, v15, v152
	s_add_u32 s20, s18, 0x88200
	s_addc_u32 s21, s19, 0
	global_store_short_d16_hi v98, v12, s[20:21]
	v_mul_f32_e32 v3, 0x3d372713, v33
	v_mul_f32_e32 v3, v33, v3
	v_fma_f32 v3, v33, v3, v33
	v_mul_f32_e32 v3, 0xbfcc422a, v3
	v_mul_f32_e32 v3, 0x3fb8aa3b, v3
	v_exp_f32_e32 v3, v3
	s_nop 0
	v_add_f32_e32 v3, 1.0, v3
	v_rcp_f32_e32 v3, v3
	s_nop 0
	v_mul_f32_e32 v3, v33, v3
	v_mul_f32_e32 v3, v26, v3
	v_bfe_u32 v12, v3, 16, 1
	v_add3_u32 v12, v3, v12, s89
	s_add_u32 s20, s18, 0x8f000
	s_addc_u32 s21, s19, 0
	global_store_short_d16_hi v98, v12, s[20:21]
	v_mul_f32_e32 v3, 0x3d372713, v34
	v_mul_f32_e32 v3, v34, v3
	v_fma_f32 v3, v34, v3, v34
	v_mul_f32_e32 v3, 0xbfcc422a, v3
	v_mul_f32_e32 v3, 0x3fb8aa3b, v3
	v_exp_f32_e32 v3, v3
	s_nop 0
	v_add_f32_e32 v3, 1.0, v3
	v_rcp_f32_e32 v3, v3
	s_nop 0
	v_mul_f32_e32 v3, v34, v3
	v_mul_f32_e32 v3, v4, v3
	v_bfe_u32 v4, v3, 16, 1
	v_add3_u32 v4, v3, v4, s89
	s_add_u32 s20, s18, 0x90600
	s_addc_u32 s21, s19, 0
	global_store_short_d16_hi v98, v4, s[20:21]
	v_mul_f32_e32 v3, 0x3d372713, v21
	v_mul_f32_e32 v3, v21, v3
	v_fma_f32 v3, v21, v3, v21
	v_mul_f32_e32 v3, 0xbfcc422a, v3
	v_mul_f32_e32 v3, 0x3fb8aa3b, v3
	v_exp_f32_e32 v3, v3
	s_nop 0
	v_add_f32_e32 v3, 1.0, v3
	v_rcp_f32_e32 v3, v3
	s_nop 0
	v_mul_f32_e32 v3, v21, v3
	v_mul_f32_e32 v3, v5, v3
	v_bfe_u32 v4, v3, 16, 1
	v_add3_u32 v4, v3, v4, s89
	s_add_u32 s20, s18, 0x91c00
	s_addc_u32 s21, s19, 0
	global_store_short_d16_hi v98, v4, s[20:21]
	v_mul_f32_e32 v3, 0x3d372713, v22
	v_mul_f32_e32 v3, v22, v3
	v_fma_f32 v3, v22, v3, v22
	v_mul_f32_e32 v3, 0xbfcc422a, v3
	v_mul_f32_e32 v3, 0x3fb8aa3b, v3
	v_exp_f32_e32 v3, v3
	s_nop 0
	v_add_f32_e32 v3, 1.0, v3
	v_rcp_f32_e32 v3, v3
	s_nop 0
	v_mul_f32_e32 v3, v22, v3
	v_mul_f32_e32 v3, v6, v3
	v_bfe_u32 v4, v3, 16, 1
	v_add3_u32 v4, v3, v4, s89
	s_add_u32 s20, s18, 0x93200
	s_addc_u32 s21, s19, 0
	global_store_short_d16_hi v98, v4, s[20:21]
	v_mul_f32_e32 v3, 0x3d372713, v23
	v_mul_f32_e32 v3, v23, v3
	v_fma_f32 v3, v23, v3, v23
	v_mul_f32_e32 v3, 0xbfcc422a, v3
	v_mul_f32_e32 v3, 0x3fb8aa3b, v3
	v_exp_f32_e32 v3, v3
	s_nop 0
	v_add_f32_e32 v3, 1.0, v3
	v_rcp_f32_e32 v3, v3
	s_nop 0
	v_mul_f32_e32 v3, v23, v3
	v_mul_f32_e32 v3, v7, v3
	v_bfe_u32 v4, v3, 16, 1
	v_add3_u32 v4, v3, v4, s89
	s_add_u32 s20, s18, 0x9a000
	s_addc_u32 s21, s19, 0
	global_store_short_d16_hi v98, v4, s[20:21]
	v_mul_f32_e32 v3, 0x3d372713, v24
	v_mul_f32_e32 v3, v24, v3
	v_fma_f32 v3, v24, v3, v24
	v_mul_f32_e32 v3, 0xbfcc422a, v3
	v_mul_f32_e32 v3, 0x3fb8aa3b, v3
	v_exp_f32_e32 v3, v3
	s_nop 0
	v_add_f32_e32 v3, 1.0, v3
	v_rcp_f32_e32 v3, v3
	s_nop 0
	v_mul_f32_e32 v3, v24, v3
	v_mul_f32_e32 v3, v8, v3
	v_bfe_u32 v4, v3, 16, 1
	v_add3_u32 v4, v3, v4, s89
	s_add_u32 s20, s18, 0x9b600
	s_addc_u32 s21, s19, 0
	global_store_short_d16_hi v98, v4, s[20:21]
	v_mul_f32_e32 v3, 0x3d372713, v20
	v_mul_f32_e32 v3, v20, v3
	v_fma_f32 v3, v20, v3, v20
	v_mul_f32_e32 v3, 0xbfcc422a, v3
	v_mul_f32_e32 v3, 0x3fb8aa3b, v3
	v_exp_f32_e32 v3, v3
	s_nop 0
	v_add_f32_e32 v3, 1.0, v3
	v_rcp_f32_e32 v3, v3
	s_nop 0
	v_mul_f32_e32 v3, v20, v3
	v_mul_f32_e32 v3, v9, v3
	v_bfe_u32 v4, v3, 16, 1
	v_add3_u32 v4, v3, v4, s89
	s_add_u32 s20, s18, 0x9cc00
	s_addc_u32 s21, s19, 0
	global_store_short_d16_hi v98, v4, s[20:21]
	v_mul_f32_e32 v3, 0x3d372713, v19
	v_mul_f32_e32 v3, v19, v3
	v_fma_f32 v3, v19, v3, v19
	v_mul_f32_e32 v3, 0xbfcc422a, v3
	v_mul_f32_e32 v3, 0x3fb8aa3b, v3
	v_exp_f32_e32 v3, v3
	s_nop 0
	v_add_f32_e32 v3, 1.0, v3
	v_rcp_f32_e32 v3, v3
	s_nop 0
	v_mul_f32_e32 v3, v19, v3
	v_mul_f32_e32 v3, v10, v3
	v_bfe_u32 v4, v3, 16, 1
	v_add3_u32 v4, v3, v4, s89
	s_add_u32 s20, s18, 0x9e200
	s_addc_u32 s21, s19, 0
	global_store_short_d16_hi v98, v4, s[20:21]
	v_mul_f32_e32 v3, 0x3d372713, v18
	v_mul_f32_e32 v3, v18, v3
	v_fma_f32 v3, v18, v3, v18
	v_mul_f32_e32 v3, 0xbfcc422a, v3
	v_mul_f32_e32 v3, 0x3fb8aa3b, v3
	v_exp_f32_e32 v3, v3
	s_nop 0
	v_add_f32_e32 v3, 1.0, v3
	v_rcp_f32_e32 v3, v3
	s_nop 0
	v_mul_f32_e32 v3, v18, v3
	v_mul_f32_e32 v3, v11, v3
	v_bfe_u32 v4, v3, 16, 1
	v_add3_u32 v4, v3, v4, s89
	s_add_u32 s20, s18, 0xa5000
	s_addc_u32 s21, s19, 0
	global_store_short_d16_hi v98, v4, s[20:21]
	v_mul_f32_e32 v3, 0x3d372713, v17
	v_mul_f32_e32 v3, v17, v3
	v_fma_f32 v3, v17, v3, v17
	v_mul_f32_e32 v3, 0xbfcc422a, v3
	v_mul_f32_e32 v3, 0x3fb8aa3b, v3
	v_exp_f32_e32 v3, v3
	s_nop 0
	v_add_f32_e32 v3, 1.0, v3
	v_rcp_f32_e32 v3, v3
	s_nop 0
	v_mul_f32_e32 v3, v17, v3
	v_mul_f32_e32 v1, v1, v3
	v_bfe_u32 v3, v1, 16, 1
	v_add3_u32 v1, v1, v3, s89
	s_add_u32 s20, s18, 0xa6600
	s_addc_u32 s21, s19, 0
	global_store_short_d16_hi v98, v1, s[20:21]
	v_mul_f32_e32 v2, 0x3d372713, v16
	v_mul_f32_e32 v2, v16, v2
	v_fma_f32 v2, v16, v2, v16
	v_mul_f32_e32 v2, 0xbfcc422a, v2
	v_mul_f32_e32 v2, 0x3fb8aa3b, v2
	v_exp_f32_e32 v2, v2
	s_nop 0
	v_add_f32_e32 v2, 1.0, v2
	v_rcp_f32_e32 v2, v2
	s_nop 0
	v_mul_f32_e32 v2, v16, v2
	v_mul_f32_e32 v0, v0, v2
	v_bfe_u32 v2, v0, 16, 1
	v_add3_u32 v2, v0, v2, s89
	s_add_u32 s20, s18, 0xa7c00
	s_addc_u32 s21, s19, 0
	global_store_short_d16_hi v98, v2, s[20:21]
	v_mul_f32_e32 v1, 0x3d372713, v148
	v_mul_f32_e32 v1, v148, v1
	v_fma_f32 v1, v148, v1, v148
	v_mul_f32_e32 v1, 0xbfcc422a, v1
	v_mul_f32_e32 v1, 0x3fb8aa3b, v1
	v_exp_f32_e32 v1, v1
	s_nop 0
	v_add_f32_e32 v1, 1.0, v1
	v_rcp_f32_e32 v1, v1
	s_nop 0
	v_mul_f32_e32 v1, v148, v1
	v_mul_f32_e32 v1, v149, v1
	v_bfe_u32 v2, v1, 16, 1
	v_add3_u32 v2, v1, v2, s89
	s_add_u32 s20, s18, 0xa9200
	s_addc_u32 s21, s19, 0
	global_store_short_d16_hi v98, v2, s[20:21]
	s_add_i32 s10, s10, 1
	s_mov_b64 s[2:3], 0
	s_waitcnt vmcnt(63) expcnt(7) lgkmcnt(15)
	s_barrier

.LBB0_2196:
	s_waitcnt vmcnt(11)
	v_lshl_add_u64 v[132:133], v[130:131], 0, s[6:7]
	s_lshl_b32 s0, s0, 6
	v_lshlrev_b32_e32 v130, 5, v243
	v_or3_b32 v130, v130, s0, v254
	v_ashrrev_i32_e32 v131, 31, v130
	v_lshl_add_u64 v[128:129], v[128:129], 0, s[50:51]
	v_lshlrev_b64 v[134:135], 2, v[130:131]
	v_lshl_add_u64 v[128:129], v[128:129], 0, v[134:135]
	s_waitcnt vmcnt(10)
	v_add_co_u32_e32 v136, vcc, 0x5000, v128
	v_lshl_add_u64 v[132:133], v[132:133], 0, v[134:135]
	s_nop 0
	v_addc_co_u32_e32 v137, vcc, 0, v129, vcc
	global_load_dword v154, v[136:137], off offset:2048
	v_add_co_u32_e32 v136, vcc, 0xb000, v128
	global_load_dword v153, v[128:129], off
	s_nop 0
	v_addc_co_u32_e32 v137, vcc, 0, v129, vcc
	v_add_co_u32_e32 v134, vcc, s94, v128
	global_load_dword v155, v[136:137], off
	s_nop 0
	v_addc_co_u32_e32 v135, vcc, 0, v129, vcc
	global_load_dword v150, v[134:135], off offset:3072
	v_add_co_u32_e32 v134, vcc, 0x8000, v128
	global_load_dword v148, v[132:133], off
	s_nop 0
	v_addc_co_u32_e32 v135, vcc, 0, v129, vcc
	v_add_co_u32_e32 v128, vcc, 0xd000, v128
	global_load_dword v151, v[134:135], off offset:1024
	s_nop 0
	v_addc_co_u32_e32 v129, vcc, 0, v129, vcc
	global_load_dword v152, v[128:129], off offset:3072
	v_add_co_u32_e32 v128, vcc, 0x2000, v132
	s_waitcnt vmcnt(10)
	v_ashrrev_i32_e32 v166, 7, v252
	v_addc_co_u32_e32 v129, vcc, 0, v133, vcc
	global_load_dword v149, v[128:129], off offset:3072
	v_lshlrev_b32_e32 v128, 2, v254
	v_lshlrev_b32_e32 v129, 10, v166
	v_lshlrev_b32_e32 v167, 9, v243
	v_cmp_eq_u32_e32 vcc, 0, v253
	v_cmp_ne_u32_e64 s[0:1], 0, v253
	s_waitcnt vmcnt(10)
	v_or3_b32 v168, v128, v167, v129
	s_barrier
	s_and_saveexec_b64 s[2:3], s[0:1]
	s_xor_b64 s[0:1], exec, s[2:3]
	ds_write_b32 v168, v31 offset:128
	s_or_saveexec_b64 s[0:1], s[0:1]
	v_mov_b32_e32 v144, v112
	v_mov_b32_e32 v145, 0
	v_mov_b32_e32 v142, v115
	v_mov_b32_e32 v143, 0
	v_mov_b32_e32 v140, v116
	v_mov_b32_e32 v141, 0
	v_mov_b32_e32 v136, v119
	v_mov_b32_e32 v137, 0
	v_mov_b32_e32 v134, v120
	v_mov_b32_e32 v135, 0
	v_mov_b32_e32 v132, v124
	v_mov_b32_e32 v133, 0
	v_mov_b32_e32 v183, 0x180
	v_mov_b32_e32 v138, v123
	v_mov_b32_e32 v139, 0
	v_mov_b32_e32 v133, v12
	v_mov_b32_e32 v135, v11
	v_mov_b32_e32 v137, v8
	v_mov_b32_e32 v141, v7
	v_mov_b32_e32 v143, v4
	v_mov_b32_e32 v145, v3
	v_mov_b32_e32 v156, v0
	v_mov_b32_e32 v157, v0
	v_mov_b32_e32 v158, v28
	v_mov_b32_e32 v159, v27
	v_mov_b32_e32 v160, v24
	v_mov_b32_e32 v161, v23
	v_mov_b32_e32 v162, v20
	v_mov_b32_e32 v163, v19
	v_mov_b32_e32 v164, v16
	v_mov_b32_e32 v165, v16
	v_mov_b32_e32 v169, v44
	v_mov_b32_e32 v170, v43
	v_mov_b32_e32 v171, v40
	s_waitcnt vmcnt(9)
	v_mov_b32_e32 v172, v39
	v_mov_b32_e32 v173, v36
	v_mov_b32_e32 v174, v35
	v_mov_b32_e32 v175, v32
	s_waitcnt vmcnt(8)
	v_mov_b32_e32 v176, v32
	v_mov_b32_e32 v177, v60
	v_mov_b32_e32 v178, v59
	v_mov_b32_e32 v179, v56
	v_mov_b32_e32 v180, v55
	v_mov_b32_e32 v181, v52
	v_mov_b32_e32 v182, v51
	v_mov_b32_e32 v184, v48
	v_mov_b32_e32 v185, v48
	v_mov_b32_e32 v189, v76
	v_mov_b32_e32 v190, v75
	v_mov_b32_e32 v191, v72
	v_mov_b32_e32 v192, v71
	v_mov_b32_e32 v193, v68
	v_mov_b32_e32 v194, v67
	v_mov_b32_e32 v195, v64
	v_mov_b32_e32 v196, v64
	v_mov_b32_e32 v197, v92
	v_mov_b32_e32 v198, v91
	v_mov_b32_e32 v199, v88
	v_mov_b32_e32 v200, v87
	v_mov_b32_e32 v201, v84
	v_mov_b32_e32 v202, v83
	v_mov_b32_e32 v203, v80
	v_mov_b32_e32 v204, v80
	v_mov_b32_e32 v209, v108
	v_mov_b32_e32 v210, v107
	v_mov_b32_e32 v211, v104
	v_mov_b32_e32 v212, v103
	v_mov_b32_e32 v213, v100
	v_mov_b32_e32 v214, v99
	v_mov_b32_e32 v215, v96
	v_mov_b32_e32 v216, v96
	v_mov_b32_e32 v186, v15
	v_mov_b32_e32 v146, v112
	v_mov_b32_e32 v147, 0
	s_xor_b64 exec, exec, s[0:1]
	s_cbranch_execz .LBB0_2182
	v_mov_b32_e32 v144, v116
	v_mov_b32_e32 v145, 0
	v_mov_b32_e32 v142, v119
	v_mov_b32_e32 v143, 0
	v_mov_b32_e32 v140, v120
	v_mov_b32_e32 v141, 0
	v_mov_b32_e32 v136, v123
	v_mov_b32_e32 v137, 0
	v_mov_b32_e32 v134, v124
	v_mov_b32_e32 v135, 0
	v_mov_b32_e32 v132, v127
	v_mov_b32_e32 v133, 0
	v_mov_b32_e32 v183, 0x100
	v_mov_b32_e32 v146, v115
	v_mov_b32_e32 v147, 0
	v_mov_b32_e32 v133, v15
	v_mov_b32_e32 v135, v15
	v_mov_b32_e32 v137, v12
	v_mov_b32_e32 v141, v11
	v_mov_b32_e32 v143, v8
	v_mov_b32_e32 v145, v7
	v_mov_b32_e32 v156, v4
	v_mov_b32_e32 v157, v3
	v_mov_b32_e32 v158, v31
	v_mov_b32_e32 v159, v31
	v_mov_b32_e32 v160, v28
	v_mov_b32_e32 v161, v27
	v_mov_b32_e32 v162, v24
	v_mov_b32_e32 v163, v23
	v_mov_b32_e32 v164, v20
	v_mov_b32_e32 v165, v19
	v_mov_b32_e32 v169, v47
	v_mov_b32_e32 v170, v47
	v_mov_b32_e32 v171, v44
	v_mov_b32_e32 v172, v43
	v_mov_b32_e32 v173, v40
	v_mov_b32_e32 v174, v39
	v_mov_b32_e32 v175, v36
	v_mov_b32_e32 v176, v35
	v_mov_b32_e32 v177, v63
	v_mov_b32_e32 v178, v63
	v_mov_b32_e32 v179, v60
	v_mov_b32_e32 v180, v59
	v_mov_b32_e32 v181, v56
	v_mov_b32_e32 v182, v55
	v_mov_b32_e32 v184, v52
	v_mov_b32_e32 v185, v51
	v_mov_b32_e32 v189, v79
	v_mov_b32_e32 v190, v79
	v_mov_b32_e32 v191, v76
	v_mov_b32_e32 v192, v75
	v_mov_b32_e32 v193, v72
	v_mov_b32_e32 v194, v71
	v_mov_b32_e32 v195, v68
	v_mov_b32_e32 v196, v67
	v_mov_b32_e32 v197, v95
	v_mov_b32_e32 v198, v95
	v_mov_b32_e32 v199, v92
	v_mov_b32_e32 v200, v91
	v_mov_b32_e32 v201, v88
	v_mov_b32_e32 v202, v87
	v_mov_b32_e32 v203, v84
	v_mov_b32_e32 v204, v83
	v_mov_b32_e32 v209, v111
	v_mov_b32_e32 v210, v111
	v_mov_b32_e32 v211, v108
	v_mov_b32_e32 v212, v107
	v_mov_b32_e32 v213, v104
	v_mov_b32_e32 v214, v103
	v_mov_b32_e32 v215, v100
	v_mov_b32_e32 v216, v99
	v_mov_b32_e32 v186, v96
	v_mov_b32_e32 v138, v127
	v_mov_b32_e32 v139, 0
	ds_write_b32 v168, v112
	s_branch .LBB0_2182
